# full stack: LDS-staged tail K loops (all but phase 12), E5B epilogue load hoist + rcp, FFN1 canon, cumsum relocation, ph_fb next-row prefetch
# speedup vs baseline: 1.0085x; 1.0085x over previous
; DI int opaque_tid() { int t = threadIdx.x; asm volatile("" : "+v"(t)); return t; }
; DI void ph_fb(const Params& p) {
;     const int lane = opaque_tid() & 63;
;     const int gw = blockIdx.x * 8 + (opaque_tid() >> 6), nw = gridDim.x * 8;
;     float* H = (float*)(p.ws + OFF_H); bf16_t* HB = (bf16_t*)(p.ws + OFF_HB);
;     float* LF = (float*)(p.ws + OFF_LOGF);
;     f32x4 w0[4][4], w1[4][4];
; #pragma unroll
;     for (int i = 0; i < 4; ++i)
; #pragma unroll
;         for (int e = 0; e < 4; ++e) {
;             const float* wp = p.ew_in + (size_t)(256 * i + 4 * lane + e) * 3080 + 3072;
;             w0[i][e] = *(const f32x4*)wp; w1[i][e] = *(const f32x4*)(wp + 4);
;         }
;     const int j8 = ((lane >> 5) & 1) * 4 + ((lane >> 4) & 1) * 2 + ((lane >> 3) & 1);
;     const float fbias = p.ef_bias[j8];
.LBB0_68:
	s_or_b64 exec, exec, s[0:1]
	v_mov_b32_e32 v129, v210
	v_mov_b32_e32 v0, v210
	s_lshl_b32 s81, s2, 3
	v_ashrrev_i32_e32 v0, 6, v0
	s_lshl_b32 s34, s58, 3
	v_add_u32_e32 v140, s81, v0
	s_waitcnt lgkmcnt(0)
	s_add_u32 s48, s56, 0xf860000
	s_mov_b32 s0, 0x8040
	s_addc_u32 s49, s57, 0
	v_cmp_gt_i32_e32 vcc, s0, v140
	s_and_saveexec_b64 s[10:11], vcc
	s_cbranch_execz .LBB0_77
	v_bfe_u32 v158, v129, 3, 3
	v_lshlrev_b32_e32 v0, 2, v158
	global_load_dword v159, v0, s[42:43]
	v_lshlrev_b32_e32 v0, 2, v129
	v_and_b32_e32 v128, 0xfc, v0
	v_mul_u32_u24_e32 v0, 0xc08, v128
	v_lshlrev_b32_e32 v142, 2, v0
	v_mov_b32_e32 v143, 0
	v_lshl_add_u64 v[0:1], s[40:41], 0, v[142:143]
	s_mov_b64 s[0:1], 0x912060
	v_lshl_add_u64 v[58:59], v[0:1], 0, s[0:1]
	s_mov_b32 s0, 0x912000
	v_add_co_u32_e32 v2, vcc, s0, v0
	s_mov_b64 s[0:1], 0x90f040
	s_nop 0
	v_addc_co_u32_e32 v3, vcc, 0, v1, vcc
	v_lshl_add_u64 v[56:57], v[0:1], 0, s[0:1]
	s_mov_b32 s0, 0x90f000
	v_add_co_u32_e32 v60, vcc, s0, v0
	s_mov_b64 s[0:1], 0x90c020
	s_nop 0
	v_addc_co_u32_e32 v61, vcc, 0, v1, vcc
	v_lshl_add_u64 v[62:63], v[0:1], 0, s[0:1]
	s_mov_b32 s0, 0x90c000
	v_add_co_u32_e32 v64, vcc, s0, v0
	s_mov_b64 s[0:1], 0x909000
	s_nop 0
	v_addc_co_u32_e32 v65, vcc, 0, v1, vcc
	v_lshl_add_u64 v[66:67], v[0:1], 0, s[0:1]
	s_mov_b32 s0, 0x909000
	v_add_co_u32_e32 v68, vcc, s0, v0
	s_mov_b64 s[0:1], 0x610060
	s_nop 0
	v_addc_co_u32_e32 v69, vcc, 0, v1, vcc
	v_lshl_add_u64 v[70:71], v[0:1], 0, s[0:1]
	s_mov_b32 s0, 0x610000
	v_add_co_u32_e32 v72, vcc, s0, v0
	s_mov_b32 s3, 0x60d000
	s_nop 0
	v_addc_co_u32_e32 v73, vcc, 0, v1, vcc
	v_add_co_u32_e32 v74, vcc, s3, v0
	s_mov_b32 s3, 0x60a000
	s_nop 0
	v_addc_co_u32_e32 v75, vcc, 0, v1, vcc
	v_add_co_u32_e32 v76, vcc, s3, v0
	s_mov_b32 s3, 0x607000
	s_nop 0
	v_addc_co_u32_e32 v77, vcc, 0, v1, vcc
	v_add_co_u32_e32 v84, vcc, s3, v0
	s_mov_b32 s3, 0x30e000
	s_nop 0
	v_addc_co_u32_e32 v85, vcc, 0, v1, vcc
	v_add_co_u32_e32 v86, vcc, s3, v0
	s_mov_b32 s3, 0x30b000
	s_nop 0
	v_addc_co_u32_e32 v87, vcc, 0, v1, vcc
	v_add_co_u32_e32 v88, vcc, s3, v0
	s_mov_b32 s3, 0x308000
	s_nop 0
	v_addc_co_u32_e32 v89, vcc, 0, v1, vcc
	v_add_co_u32_e32 v90, vcc, s3, v0
	s_mov_b32 s3, 0x305000
	s_nop 0
	v_addc_co_u32_e32 v91, vcc, 0, v1, vcc
	v_add_co_u32_e32 v96, vcc, s3, v0
	s_mov_b32 s3, 0xc000
	s_nop 0
	v_addc_co_u32_e32 v97, vcc, 0, v1, vcc
	v_add_co_u32_e32 v104, vcc, s3, v0
	s_mov_b32 s3, 0x9000
	s_nop 0
	v_addc_co_u32_e32 v105, vcc, 0, v1, vcc
	v_add_co_u32_e32 v106, vcc, s3, v0
	s_movk_i32 s3, 0x6000
	s_nop 0
	v_addc_co_u32_e32 v107, vcc, 0, v1, vcc
	v_add_co_u32_e32 v112, vcc, s3, v0
	s_movk_i32 s3, 0x3000
	s_nop 0
	v_addc_co_u32_e32 v113, vcc, 0, v1, vcc
	s_mov_b64 s[0:1], 0x60d040
	s_mov_b64 s[4:5], 0x60a020
	s_mov_b64 s[6:7], 0x607000
	s_mov_b64 s[8:9], 0x30e060
	s_mov_b64 s[12:13], 0x30b040
	s_mov_b64 s[14:15], 0x308020
	s_mov_b64 s[16:17], 0x305000
	s_mov_b64 s[18:19], 0xc060
	s_mov_b64 s[20:21], 0x9040
	s_mov_b64 s[22:23], 0x6020
	s_mov_b64 s[24:25], 0x3000
	v_add_co_u32_e32 v120, vcc, s3, v0
	v_lshl_add_u64 v[78:79], v[0:1], 0, s[0:1]
	s_nop 0
	v_addc_co_u32_e32 v121, vcc, 0, v1, vcc
	v_lshl_add_u64 v[80:81], v[0:1], 0, s[4:5]
	v_lshl_add_u64 v[92:93], v[0:1], 0, s[6:7]
	v_lshl_add_u64 v[94:95], v[0:1], 0, s[8:9]
	v_lshl_add_u64 v[98:99], v[0:1], 0, s[12:13]
	v_lshl_add_u64 v[100:101], v[0:1], 0, s[14:15]
	v_lshl_add_u64 v[102:103], v[0:1], 0, s[16:17]
	v_lshl_add_u64 v[108:109], v[0:1], 0, s[18:19]
	v_lshl_add_u64 v[110:111], v[0:1], 0, s[20:21]
	v_lshl_add_u64 v[116:117], v[0:1], 0, s[22:23]
	v_lshl_add_u64 v[124:125], v[0:1], 0, s[24:25]
	global_load_dwordx4 v[0:3], v[2:3], off offset:96
	s_nop 0
	global_load_dwordx4 v[4:7], v[58:59], off offset:16
	global_load_dwordx4 v[8:11], v[60:61], off offset:64
	global_load_dwordx4 v[12:15], v[56:57], off offset:16
	global_load_dwordx4 v[16:19], v[64:65], off offset:32
	global_load_dwordx4 v[20:23], v[62:63], off offset:16
	global_load_dwordx4 v[24:27], v[68:69], off
	global_load_dwordx4 v[28:31], v[66:67], off offset:16
	global_load_dwordx4 v[32:35], v[72:73], off offset:96
	global_load_dwordx4 v[36:39], v[70:71], off offset:16
	global_load_dwordx4 v[40:43], v[74:75], off offset:64
	global_load_dwordx4 v[44:47], v[78:79], off offset:16
; DI void ph_fb(const Params& p) {
;     ...
;     const int j8 = ((lane >> 5) & 1) * 4 + ((lane >> 4) & 1) * 2 + ((lane >> 3) & 1);
;     const float fbias = p.ef_bias[j8];
;     for (int m = gw; m < MT; m += nw) {
;         const int b_ = m / LT, pos_ = m - b_ * LT;
;         const float* hrow = pos_ < 16 ? p.meta + (size_t)pos_ * 1024 : p.x + ((size_t)b_ * 8192 + (pos_ - 16)) * 1024;
;         f32x4 hv[4];
; #pragma unroll
;         for (int i = 0; i < 4; ++i) hv[i] = *(const f32x4*)(hrow + 256 * i + 4 * lane);
	global_load_dwordx4 v[48:51], v[76:77], off offset:32
	global_load_dwordx4 v[52:55], v[80:81], off offset:16
	global_load_dwordx4 v[56:59], v[84:85], off
	global_load_dwordx4 v[60:63], v[92:93], off offset:16
	global_load_dwordx4 v[64:67], v[86:87], off offset:96
	global_load_dwordx4 v[68:71], v[94:95], off offset:16
	global_load_dwordx4 v[72:75], v[88:89], off offset:64
	global_load_dwordx4 v[76:79], v[98:99], off offset:16
	global_load_dwordx4 v[80:83], v[90:91], off offset:32
	s_nop 0
	global_load_dwordx4 v[84:87], v[100:101], off offset:16
	global_load_dwordx4 v[88:91], v[96:97], off
	global_load_dwordx4 v[92:95], v[102:103], off offset:16
	s_nop 0
	global_load_dwordx4 v[96:99], v[104:105], off offset:96
	global_load_dwordx4 v[100:103], v[108:109], off offset:16
	s_nop 0
	global_load_dwordx4 v[104:107], v[106:107], off offset:64
	s_nop 0
	global_load_dwordx4 v[108:111], v[110:111], off offset:16
	s_nop 0
	global_load_dwordx4 v[112:115], v[112:113], off offset:32
	s_nop 0
	global_load_dwordx4 v[116:119], v[116:117], off offset:16
	s_nop 0
	global_load_dwordx4 v[120:123], v[120:121], off
	s_nop 0
	global_load_dwordx4 v[124:127], v[124:125], off offset:16
	v_and_b32_e32 v130, 32, v129
	v_cmp_eq_u32_e64 s[0:1], 0, v130
	v_and_b32_e32 v130, 16, v129
	v_cmp_eq_u32_e64 s[4:5], 0, v130
	v_and_b32_e32 v130, 8, v129
	v_cmp_eq_u32_e64 s[6:7], 0, v130
	v_mbcnt_lo_u32_b32 v130, -1, 0
	v_mbcnt_hi_u32_b32 v130, -1, v130
	v_and_b32_e32 v132, 64, v130
	v_xor_b32_e32 v131, 32, v130
	v_add_u32_e32 v132, 64, v132
	v_cmp_lt_i32_e32 vcc, v131, v132
	v_xor_b32_e32 v133, 16, v130
	v_xor_b32_e32 v134, 8, v130
	v_cndmask_b32_e32 v131, v130, v131, vcc
	v_cmp_lt_i32_e32 vcc, v133, v132
	v_xor_b32_e32 v135, 4, v130
	v_xor_b32_e32 v136, 2, v130
	v_cndmask_b32_e32 v133, v130, v133, vcc
	v_cmp_lt_i32_e32 vcc, v134, v132
	v_xor_b32_e32 v137, 1, v130
	v_ashrrev_i32_e32 v141, 31, v140
	v_cndmask_b32_e32 v134, v130, v134, vcc
	v_cmp_lt_i32_e32 vcc, v135, v132
	v_lshlrev_b64 v[144:145], 12, v[140:141]
	v_lshlrev_b64 v[146:147], 11, v[140:141]
	v_cndmask_b32_e32 v135, v130, v135, vcc
	v_cmp_lt_i32_e32 vcc, v136, v132
	s_ashr_i32 s35, s34, 31
	v_lshlrev_b32_e32 v142, 2, v128
	v_cndmask_b32_e32 v136, v130, v136, vcc
	v_cmp_lt_i32_e32 vcc, v137, v132
	v_and_b32_e32 v132, 7, v129
	v_and_b32_e32 v129, 63, v129
	v_cndmask_b32_e32 v130, v130, v137, vcc
	v_cmp_eq_u32_e64 s[8:9], 0, v132
	v_lshl_or_b32 v144, v129, 4, v144
	v_lshl_or_b32 v146, v129, 3, v146
	v_lshlrev_b32_e32 v141, 2, v131
	v_lshlrev_b32_e32 v160, 2, v133
	v_lshlrev_b32_e32 v161, 2, v134
	v_lshlrev_b32_e32 v162, 2, v135
	v_lshlrev_b32_e32 v163, 2, v136
	v_lshlrev_b32_e32 v164, 2, v130
	s_lshl_b64 s[12:13], s[34:35], 12
	s_lshl_b64 s[14:15], s[34:35], 11
	s_mov_b64 s[16:17], 0
	s_mov_b32 s3, 0x7fc01ff1
	s_movk_i32 s20, 0xdff0
	s_mov_b32 s21, 0xb840000
	s_mov_b32 s22, 0xbfb8aa3b
	s_mov_b32 s23, 0xb2a5705f
	s_mov_b32 s24, 0x42ce8ed0
	s_mov_b32 s25, 0xc2b17218
	s_mov_b32 s26, 0x7f800000
	s_mov_b32 s27, 0x3f2aaaab
	s_mov_b32 s28, 0x3f317218
	s_mov_b32 s29, 0x33800000
	s_mov_b32 s35, 0x803f
	v_mov_b32_e32 v165, 0x3ecc95a3
	v_mov_b32_e32 v166, 0x7f800000
	v_mov_b32_e32 v148, 0x3f317218
	v_min_i32_e32 v212, s35, v140
	v_mul_hi_i32 v213, v212, s3
	v_lshrrev_b32_e32 v220, 31, v213
	v_ashrrev_i32_e32 v213, 12, v213
	v_add_u32_e32 v216, v213, v220
	v_mad_i32_i24 v218, v216, s20, v212
	v_cmp_lt_i32_e32 vcc, 15, v218
	v_mov_b64_e32 v[214:215], s[38:39]
	s_and_saveexec_b64 s[88:89], vcc
	s_xor_b64 s[88:89], exec, s[88:89]
	v_ashrrev_i32_e32 v217, 31, v216
	v_lshlrev_b64 v[214:215], 25, v[216:217]
	v_add_u32_e32 v220, -16, v218
	v_mov_b32_e32 v221, v143
	v_lshl_add_u64 v[214:215], s[36:37], 0, v[214:215]
	s_andn2_saveexec_b64 s[88:89], s[88:89]
	v_ashrrev_i32_e32 v219, 31, v218
	v_mov_b64_e32 v[220:221], v[218:219]
	s_or_b64 exec, exec, s[88:89]
	v_lshlrev_b64 v[220:221], 12, v[220:221]
	v_lshl_add_u64 v[214:215], v[214:215], 0, v[220:221]
	v_lshl_add_u64 v[222:223], v[214:215], 0, v[142:143]
	global_load_dwordx4 v[224:227], v[222:223], off
	global_load_dwordx4 v[228:231], v[222:223], off offset:1024
	global_load_dwordx4 v[232:235], v[222:223], off offset:2048
	global_load_dwordx4 v[236:239], v[222:223], off offset:3072
	s_waitcnt vmcnt(0)
	s_branch .LBB0_71

; DI unsigned cvt_pk(float lo, float hi) { f32x2 v = {lo, hi}; bf16x2v b = __builtin_convertvector(v, bf16x2v); return __builtin_bit_cast(unsigned, b); }
; DI void ph_fb(const Params& p) {
;     ...
;     for (int m = gw; m < MT; m += nw) {
;         const int b_ = m / LT, pos_ = m - b_ * LT;
;         const float* hrow = pos_ < 16 ? p.meta + (size_t)pos_ * 1024 : p.x + ((size_t)b_ * 8192 + (pos_ - 16)) * 1024;
;         f32x4 hv[4];
; #pragma unroll
;         for (int i = 0; i < 4; ++i) hv[i] = *(const f32x4*)(hrow + 256 * i + 4 * lane);
; #pragma unroll
;         for (int i = 0; i < 4; ++i) {
;             *(f32x4*)(H + (size_t)m * 1024 + 256 * i + 4 * lane) = hv[i];
;             u32x2 wv; wv[0] = cvt_pk(hv[i][0], hv[i][1]); wv[1] = cvt_pk(hv[i][2], hv[i][3]);
;             *(u32x2*)(HB + (size_t)m * 1024 + 256 * i + 4 * lane) = wv;
;         }
;         float a[8];
; #pragma unroll
;         for (int j = 0; j < 8; ++j) a[j] = 0.f;
; #pragma unroll
;         for (int i = 0; i < 4; ++i)
; #pragma unroll
;             for (int e = 0; e < 4; ++e) {
;                 const float x = hv[i][e];
;                 a[0] += x * w0[i][e][0]; a[1] += x * w0[i][e][1]; a[2] += x * w0[i][e][2]; a[3] += x * w0[i][e][3];
;                 a[4] += x * w1[i][e][0]; a[5] += x * w1[i][e][1]; a[6] += x * w1[i][e][2]; a[7] += x * w1[i][e][3];
;             }
.LBB0_71:
	s_waitcnt vmcnt(8)
	v_mul_hi_i32 v128, v140, s3
	s_waitcnt lgkmcnt(0)
	v_lshrrev_b32_e32 v129, 31, v128
	v_ashrrev_i32_e32 v128, 12, v128
	v_add_u32_e32 v152, v128, v129
	v_mad_i32_i24 v150, v152, s20, v140
	v_cmp_lt_i32_e32 vcc, 15, v150
	v_mov_b64_e32 v[128:129], s[38:39]
	s_and_saveexec_b64 s[18:19], vcc
	s_xor_b64 s[18:19], exec, s[18:19]
	v_ashrrev_i32_e32 v153, 31, v152
	v_lshlrev_b64 v[128:129], 25, v[152:153]
	v_add_u32_e32 v130, -16, v150
	v_mov_b32_e32 v131, v143
	v_lshl_add_u64 v[128:129], s[36:37], 0, v[128:129]
	s_andn2_saveexec_b64 s[18:19], s[18:19]
	v_ashrrev_i32_e32 v151, 31, v150
	v_mov_b64_e32 v[130:131], v[150:151]
	s_or_b64 exec, exec, s[18:19]
	v_lshlrev_b64 v[130:131], 12, v[130:131]
	v_lshl_add_u64 v[128:129], v[128:129], 0, v[130:131]
	v_lshl_add_u64 v[154:155], v[128:129], 0, v[142:143]
	v_mov_b32_e32 v136, v224
	v_mov_b32_e32 v137, v225
	v_mov_b32_e32 v138, v226
	v_mov_b32_e32 v139, v227
	v_mov_b32_e32 v128, v228
	v_mov_b32_e32 v129, v229
	v_mov_b32_e32 v130, v230
	v_mov_b32_e32 v131, v231
	v_mov_b32_e32 v132, v232
	v_mov_b32_e32 v133, v233
	v_mov_b32_e32 v134, v234
	v_mov_b32_e32 v135, v235
	v_mov_b32_e32 v168, v236
	v_mov_b32_e32 v169, v237
	v_mov_b32_e32 v170, v238
	v_mov_b32_e32 v171, v239
	v_add_u32_e32 v212, s34, v140
	v_min_i32_e32 v212, s35, v212
	v_mul_hi_i32 v213, v212, s3
	v_lshrrev_b32_e32 v220, 31, v213
	v_ashrrev_i32_e32 v213, 12, v213
	v_add_u32_e32 v216, v213, v220
	v_mad_i32_i24 v218, v216, s20, v212
	v_cmp_lt_i32_e32 vcc, 15, v218
	v_mov_b64_e32 v[214:215], s[38:39]
	s_and_saveexec_b64 s[88:89], vcc
	s_xor_b64 s[88:89], exec, s[88:89]
	v_ashrrev_i32_e32 v217, 31, v216
	v_lshlrev_b64 v[214:215], 25, v[216:217]
	v_add_u32_e32 v220, -16, v218
	v_mov_b32_e32 v221, v143
	v_lshl_add_u64 v[214:215], s[36:37], 0, v[214:215]
	s_andn2_saveexec_b64 s[88:89], s[88:89]
	v_ashrrev_i32_e32 v219, 31, v218
	v_mov_b64_e32 v[220:221], v[218:219]
	s_or_b64 exec, exec, s[88:89]
	v_lshlrev_b64 v[220:221], 12, v[220:221]
	v_lshl_add_u64 v[214:215], v[214:215], 0, v[220:221]
	v_lshl_add_u64 v[222:223], v[214:215], 0, v[142:143]
	global_load_dwordx4 v[224:227], v[222:223], off
	global_load_dwordx4 v[228:231], v[222:223], off offset:1024
	global_load_dwordx4 v[232:235], v[222:223], off offset:2048
	global_load_dwordx4 v[236:239], v[222:223], off offset:3072
	v_lshl_add_u64 v[156:157], s[56:57], 0, v[144:145]
	v_add_co_u32_e32 v156, vcc, 0x3800000, v156
	v_lshl_add_u64 v[172:173], s[56:57], 0, v[146:147]
	s_nop 0
	v_addc_co_u32_e32 v157, vcc, 0, v157, vcc
	v_fma_f32 v149, v120, v136, 0
	v_fma_f32 v174, v124, v136, 0
	v_fmac_f32_e32 v149, v112, v137
	v_fmac_f32_e32 v174, v116, v137
	v_fmac_f32_e32 v149, v104, v138
	v_fmac_f32_e32 v174, v108, v138
	v_fmac_f32_e32 v149, v96, v139
	v_fmac_f32_e32 v174, v100, v139
	v_fmac_f32_e32 v149, v88, v128
	v_fmac_f32_e32 v174, v92, v128
	v_fmac_f32_e32 v149, v80, v129
	v_fmac_f32_e32 v174, v84, v129
	v_fma_f32 v151, v121, v136, 0
	v_fma_f32 v175, v125, v136, 0
	v_fmac_f32_e32 v149, v72, v130
	v_fmac_f32_e32 v174, v76, v130
	v_fma_f32 v153, v122, v136, 0
	v_fma_f32 v176, v126, v136, 0
	v_fmac_f32_e32 v151, v113, v137
	v_fmac_f32_e32 v175, v117, v137
	v_fmac_f32_e32 v149, v64, v131
	v_fmac_f32_e32 v174, v68, v131
	global_store_dwordx4 v[156:157], v[136:139], off
	v_cvt_pk_bf16_f32 v154, v136, v137
	v_fma_f32 v167, v123, v136, 0
	v_fma_f32 v136, v127, v136, 0
	v_fmac_f32_e32 v153, v114, v137
	v_fmac_f32_e32 v176, v118, v137
	v_fmac_f32_e32 v151, v105, v138
	v_fmac_f32_e32 v175, v109, v138
	v_fmac_f32_e32 v149, v56, v132
	v_fmac_f32_e32 v174, v60, v132
	v_fmac_f32_e32 v167, v115, v137
	v_fmac_f32_e32 v136, v119, v137
	v_fmac_f32_e32 v153, v106, v138
	v_fmac_f32_e32 v176, v110, v138
	v_fmac_f32_e32 v151, v97, v139
	v_fmac_f32_e32 v175, v101, v139
	v_fmac_f32_e32 v149, v48, v133
	v_fmac_f32_e32 v174, v52, v133
	v_fmac_f32_e32 v167, v107, v138
	v_fmac_f32_e32 v136, v111, v138
	v_fmac_f32_e32 v153, v98, v139
	v_fmac_f32_e32 v176, v102, v139
	v_fmac_f32_e32 v151, v89, v128
	v_fmac_f32_e32 v175, v93, v128
	v_fmac_f32_e32 v149, v40, v134
	v_fmac_f32_e32 v174, v44, v134
	v_fmac_f32_e32 v167, v99, v139
	v_fmac_f32_e32 v136, v103, v139
	v_fmac_f32_e32 v153, v90, v128
	v_fmac_f32_e32 v176, v94, v128
	v_fmac_f32_e32 v151, v81, v129
	v_fmac_f32_e32 v175, v85, v129
	v_fmac_f32_e32 v149, v32, v135
	v_fmac_f32_e32 v174, v36, v135
	v_fmac_f32_e32 v167, v91, v128
	v_fmac_f32_e32 v136, v95, v128
	v_fmac_f32_e32 v153, v82, v129
	v_fmac_f32_e32 v176, v86, v129
	v_fmac_f32_e32 v151, v73, v130
	v_fmac_f32_e32 v175, v77, v130
	v_fmac_f32_e32 v149, v24, v168
	v_fmac_f32_e32 v174, v28, v168
	v_fmac_f32_e32 v167, v83, v129
	v_fmac_f32_e32 v136, v87, v129
	v_fmac_f32_e32 v153, v74, v130
	v_fmac_f32_e32 v176, v78, v130
	v_fmac_f32_e32 v151, v65, v131
	v_fmac_f32_e32 v175, v69, v131
	v_fmac_f32_e32 v149, v16, v169
	v_fmac_f32_e32 v174, v20, v169
	v_fmac_f32_e32 v167, v75, v130
	v_fmac_f32_e32 v136, v79, v130
	v_fmac_f32_e32 v153, v66, v131
	v_fmac_f32_e32 v176, v70, v131
	v_fmac_f32_e32 v151, v57, v132
	v_fmac_f32_e32 v175, v61, v132
	v_fmac_f32_e32 v149, v8, v170
	v_fmac_f32_e32 v174, v12, v170
	v_fmac_f32_e32 v167, v67, v131
	v_fmac_f32_e32 v136, v71, v131
	v_fmac_f32_e32 v149, v0, v171
	v_fmac_f32_e32 v174, v4, v171
	v_fmac_f32_e32 v151, v49, v133
	v_fmac_f32_e32 v175, v53, v133
	v_fmac_f32_e32 v153, v58, v132
	v_fmac_f32_e32 v176, v62, v132
	v_cndmask_b32_e64 v137, v149, v174, s[0:1]
	v_fmac_f32_e32 v151, v41, v134
	v_fmac_f32_e32 v175, v45, v134
	v_fmac_f32_e32 v153, v50, v133
	v_fmac_f32_e32 v176, v54, v133
	v_fmac_f32_e32 v167, v59, v132
	v_fmac_f32_e32 v136, v63, v132
	ds_bpermute_b32 v137, v141, v137
	v_fmac_f32_e32 v151, v33, v135
	v_fmac_f32_e32 v175, v37, v135
	v_fmac_f32_e32 v153, v42, v134
	v_fmac_f32_e32 v176, v46, v134
	v_fmac_f32_e32 v167, v51, v133
	v_fmac_f32_e32 v136, v55, v133
	v_fmac_f32_e32 v151, v25, v168
	v_fmac_f32_e32 v175, v29, v168
	v_fmac_f32_e32 v153, v34, v135
	v_fmac_f32_e32 v176, v38, v135
	v_fmac_f32_e32 v167, v43, v134
	v_fmac_f32_e32 v136, v47, v134
	v_fmac_f32_e32 v151, v17, v169
	v_fmac_f32_e32 v175, v21, v169
	v_fmac_f32_e32 v153, v26, v168
	v_fmac_f32_e32 v176, v30, v168
	v_fmac_f32_e32 v167, v35, v135
	v_fmac_f32_e32 v136, v39, v135
	v_fmac_f32_e32 v151, v9, v170
	v_fmac_f32_e32 v175, v13, v170
	v_fmac_f32_e32 v153, v18, v169
	v_fmac_f32_e32 v176, v22, v169
	v_fmac_f32_e32 v167, v27, v168
	v_fmac_f32_e32 v136, v31, v168
	v_cvt_pk_bf16_f32 v155, v138, v139
	v_cndmask_b32_e64 v138, v174, v149, s[0:1]
	v_fmac_f32_e32 v151, v1, v171
	v_fmac_f32_e32 v175, v5, v171
	v_fmac_f32_e32 v153, v10, v170
	v_fmac_f32_e32 v176, v14, v170
	v_fmac_f32_e32 v167, v19, v169
	v_fmac_f32_e32 v136, v23, v169
	s_waitcnt lgkmcnt(0)
; DI unsigned cvt_pk(float lo, float hi) { f32x2 v = {lo, hi}; bf16x2v b = __builtin_convertvector(v, bf16x2v); return __builtin_bit_cast(unsigned, b); }
; DI void ph_fb(const Params& p) {
;     ...
;         for (int i = 0; i < 4; ++i) {
;             *(f32x4*)(H + (size_t)m * 1024 + 256 * i + 4 * lane) = hv[i];
;             u32x2 wv; wv[0] = cvt_pk(hv[i][0], hv[i][1]); wv[1] = cvt_pk(hv[i][2], hv[i][3]);
;             *(u32x2*)(HB + (size_t)m * 1024 + 256 * i + 4 * lane) = wv;
;         }
;     ...
;         const bool b5 = (lane & 32) != 0, b4 = (lane & 16) != 0, b3 = (lane & 8) != 0;
;         float c4[4];
; #pragma unroll
;         for (int j = 0; j < 4; ++j) { const float send = b5 ? a[j] : a[j + 4]; const float keep = b5 ? a[j + 4] : a[j]; c4[j] = keep + __shfl_xor(send, 32); }
;         float c2[2];
; #pragma unroll
;         for (int j = 0; j < 2; ++j) { const float send = b4 ? c4[j] : c4[j + 2]; const float keep = b4 ? c4[j + 2] : c4[j]; c2[j] = keep + __shfl_xor(send, 16); }
;         float v;
;         { const float send = b3 ? c2[0] : c2[1]; const float keep = b3 ? c2[1] : c2[0]; v = keep + __shfl_xor(send, 8); }
;         v += __shfl_xor(v, 4); v += __shfl_xor(v, 2); v += __shfl_xor(v, 1);
	v_add_f32_e32 v137, v138, v137
	v_cndmask_b32_e64 v138, v151, v175, s[0:1]
	v_fmac_f32_e32 v153, v2, v171
	v_fmac_f32_e32 v176, v6, v171
	v_fmac_f32_e32 v167, v11, v170
	v_fmac_f32_e32 v136, v15, v170
	ds_bpermute_b32 v138, v141, v138
	v_cndmask_b32_e64 v149, v153, v176, s[0:1]
	v_fmac_f32_e32 v167, v3, v171
	v_fmac_f32_e32 v136, v7, v171
	v_cndmask_b32_e64 v139, v175, v151, s[0:1]
	ds_bpermute_b32 v149, v141, v149
	v_cndmask_b32_e64 v151, v167, v136, s[0:1]
	ds_bpermute_b32 v151, v141, v151
	s_waitcnt lgkmcnt(2)
	v_add_f32_e32 v138, v139, v138
	v_cndmask_b32_e64 v139, v176, v153, s[0:1]
	s_waitcnt lgkmcnt(1)
	v_add_f32_e32 v139, v139, v149
	v_cndmask_b32_e64 v136, v136, v167, s[0:1]
	s_waitcnt lgkmcnt(0)
	v_add_f32_e32 v149, v136, v151
	v_cndmask_b32_e64 v136, v137, v139, s[4:5]
	ds_bpermute_b32 v151, v160, v136
	v_cndmask_b32_e64 v136, v138, v149, s[4:5]
	ds_bpermute_b32 v153, v160, v136
	v_cndmask_b32_e64 v137, v139, v137, s[4:5]
	v_add_co_u32_e32 v136, vcc, s21, v172
	s_waitcnt lgkmcnt(1)
	v_add_f32_e32 v139, v137, v151
	v_cndmask_b32_e64 v137, v149, v138, s[4:5]
	s_waitcnt lgkmcnt(0)
	v_add_f32_e32 v138, v137, v153
	v_cndmask_b32_e64 v137, v139, v138, s[6:7]
	ds_bpermute_b32 v149, v161, v137
	v_cndmask_b32_e64 v138, v138, v139, s[6:7]
	v_addc_co_u32_e32 v137, vcc, 0, v173, vcc
	global_store_dwordx2 v[136:137], v[154:155], off
	s_waitcnt lgkmcnt(0)
	v_add_f32_e32 v149, v138, v149
	ds_bpermute_b32 v151, v162, v149
	v_cvt_pk_bf16_f32 v138, v128, v129
	v_cvt_pk_bf16_f32 v139, v130, v131
	global_store_dwordx4 v[156:157], v[128:131], off offset:1024
	global_store_dwordx2 v[136:137], v[138:139], off offset:512
	global_store_dwordx4 v[156:157], v[132:135], off offset:2048
	s_waitcnt lgkmcnt(0)
	v_add_f32_e32 v130, v149, v151
	ds_bpermute_b32 v131, v163, v130
	v_cvt_pk_bf16_f32 v128, v132, v133
	v_cvt_pk_bf16_f32 v129, v134, v135
	global_store_dwordx2 v[136:137], v[128:129], off offset:1024
	global_store_dwordx4 v[156:157], v[168:171], off offset:3072
	s_waitcnt lgkmcnt(0)
	v_add_f32_e32 v128, v130, v131
	ds_bpermute_b32 v129, v164, v128
	v_cvt_pk_bf16_f32 v130, v168, v169
	v_cvt_pk_bf16_f32 v131, v170, v171
	global_store_dwordx2 v[136:137], v[130:131], off offset:1536
	s_and_saveexec_b64 s[18:19], s[8:9]
	s_cbranch_execz .LBB0_70
; DI void ph_fb(const Params& p) {
;     ...
;         if ((lane & 7) == 0) {
;             const float xx = v + fbias;
;             const float ls = fminf(xx, 0.f) - log1pf(expf(-fabsf(xx)));
;             const int b = m / LT, pos = m - b * LT;
;             LF[(size_t)(b * 8 + j8) * LP + pos] = ls;
;         }
	s_waitcnt lgkmcnt(0)
	v_add_f32_e32 v128, v128, v129
	v_add_f32_e32 v128, v159, v128
	v_mul_f32_e64 v129, |v128|, s22
	v_fma_f32 v130, |v128|, s22, -v129
	v_rndne_f32_e32 v131, v129
	v_fma_f32 v130, |v128|, s23, v130
	v_sub_f32_e32 v129, v129, v131
	v_add_f32_e32 v129, v129, v130
	v_exp_f32_e32 v129, v129
	v_cvt_i32_f32_e32 v130, v131
	v_cmp_ngt_f32_e64 vcc, |v128|, s24
	v_min_f32_e32 v151, 0, v128
	v_ldexp_f32 v129, v129, v130
	v_cndmask_b32_e32 v129, 0, v129, vcc
	v_cmp_nlt_f32_e64 vcc, |v128|, s25
	s_nop 1
	v_cndmask_b32_e32 v153, v166, v129, vcc
	v_add_f32_e32 v130, 1.0, v153
	v_add_f32_e32 v128, -1.0, v130
	v_sub_f32_e32 v129, v128, v130
	v_add_f32_e32 v129, 1.0, v129
	v_sub_f32_e32 v128, v153, v128
	v_add_f32_e32 v131, v128, v129
	v_frexp_mant_f32_e32 v132, v130
	v_cvt_f64_f32_e32 v[128:129], v130
	v_frexp_exp_i32_f64_e32 v128, v[128:129]
	v_cmp_gt_f32_e32 vcc, s27, v132
	s_nop 1
	v_subbrev_co_u32_e32 v136, vcc, 0, v128, vcc
	v_sub_u32_e32 v128, 0, v136
	v_ldexp_f32 v129, v130, v128
	v_add_f32_e32 v130, -1.0, v129
	v_add_f32_e32 v132, 1.0, v129
	v_ldexp_f32 v128, v131, v128
	v_add_f32_e32 v131, 1.0, v130
	v_add_f32_e32 v133, -1.0, v132
	v_sub_f32_e32 v131, v129, v131
	v_sub_f32_e32 v129, v129, v133
	v_add_f32_e32 v131, v128, v131
	v_add_f32_e32 v128, v128, v129
	v_add_f32_e32 v137, v132, v128
	v_rcp_f32_e32 v139, v137
	v_sub_f32_e32 v129, v132, v137
	v_add_f32_e32 v138, v128, v129
	v_add_f32_e32 v129, v130, v131
	v_mul_f32_e32 v154, v129, v139
	v_sub_f32_e32 v128, v130, v129
	v_mul_f32_e32 v130, v137, v154
	v_fma_f32 v132, v154, v137, -v130
	v_fmac_f32_e32 v132, v154, v138
	v_add_f32_e32 v149, v131, v128
	v_add_f32_e32 v128, v130, v132
	v_sub_f32_e32 v131, v129, v128
	v_pk_add_f32 v[134:135], v[128:129], v[130:131] neg_lo:[0,1] neg_hi:[0,1]
	v_mov_b32_e32 v133, v128
	v_pk_add_f32 v[128:129], v[134:135], v[132:133] neg_lo:[0,1] neg_hi:[0,1]
	v_cmp_neq_f32_e32 vcc, s26, v153
	v_add_f32_e32 v129, v149, v129
	v_add_f32_e32 v128, v128, v129
	v_add_f32_e32 v129, v131, v128
	v_mul_f32_e32 v149, v139, v129
	v_mul_f32_e32 v130, v137, v149
	v_fma_f32 v132, v149, v137, -v130
	v_fmac_f32_e32 v132, v149, v138
	v_sub_f32_e32 v131, v131, v129
	v_add_f32_e32 v137, v128, v131
	v_add_f32_e32 v128, v130, v132
	v_sub_f32_e32 v131, v129, v128
	v_pk_add_f32 v[134:135], v[128:129], v[130:131] neg_lo:[0,1] neg_hi:[0,1]
	v_mov_b32_e32 v133, v128
	v_pk_add_f32 v[128:129], v[134:135], v[132:133] neg_lo:[0,1] neg_hi:[0,1]
	s_nop 0
	v_add_f32_e32 v129, v137, v129
	v_add_f32_e32 v128, v128, v129
	v_add_f32_e32 v129, v154, v149
	v_add_f32_e32 v128, v131, v128
	v_sub_f32_e32 v130, v129, v154
	v_mul_f32_e32 v128, v139, v128
	v_sub_f32_e32 v130, v149, v130
	v_add_f32_e32 v130, v130, v128
	v_add_f32_e32 v132, v129, v130
	v_mul_f32_e32 v133, v132, v132
	v_fmamk_f32 v128, v133, 0x3e9b6dac, v165
	v_fmaak_f32 v149, v133, v128, 0x3f2aaada
	v_cvt_f32_i32_e32 v128, v136
	v_sub_f32_e32 v129, v132, v129
	v_sub_f32_e32 v129, v130, v129
	v_ldexp_f32 v134, v129, 1
	v_mul_f32_e32 v129, v132, v133
	v_ldexp_f32 v131, v132, 1
	v_pk_mul_f32 v[132:133], v[128:129], v[148:149]
	s_nop 0
	v_fma_f32 v130, v128, s28, -v132
	v_fmac_f32_e32 v130, 0xb102e308, v128
	v_pk_add_f32 v[128:129], v[132:133], v[130:131]
	s_nop 0
	v_sub_f32_e32 v131, v129, v131
	v_sub_f32_e32 v131, v133, v131
	v_add_f32_e32 v135, v134, v131
	v_mov_b32_e32 v134, v132
	v_pk_add_f32 v[132:133], v[128:129], v[132:133] neg_lo:[0,1] neg_hi:[0,1]
	v_pk_add_f32 v[136:137], v[128:129], v[134:135]
	v_mov_b32_e32 v131, v128
	v_mov_b32_e32 v133, v137
	v_pk_add_f32 v[138:139], v[130:131], v[132:133] neg_lo:[0,1] neg_hi:[0,1]
	v_pk_add_f32 v[130:131], v[130:131], v[132:133]
	v_mov_b32_e32 v134, v135
	v_pk_add_f32 v[132:133], v[130:131], v[128:129] op_sel:[1,0] op_sel_hi:[0,1] neg_lo:[0,1] neg_hi:[0,1]
	v_pk_add_f32 v[154:155], v[136:137], v[132:133] op_sel_hi:[1,0] neg_lo:[0,1] neg_hi:[0,1]
	v_mov_b32_e32 v136, v137
	v_mov_b32_e32 v137, v131
	v_pk_mov_b32 v[132:133], v[128:129], v[132:133] op_sel:[1,0]
	v_mov_b32_e32 v135, v128
	v_pk_add_f32 v[132:133], v[136:137], v[132:133] neg_lo:[0,1] neg_hi:[0,1]
	v_mov_b32_e32 v154, v138
	v_pk_add_f32 v[128:129], v[134:135], v[132:133] neg_lo:[0,1] neg_hi:[0,1]
	v_mov_b32_e32 v139, v131
	v_pk_add_f32 v[132:133], v[154:155], v[128:129]
	s_nop 0
	v_pk_add_f32 v[134:135], v[132:133], v[132:133] op_sel:[0,1] op_sel_hi:[1,0]
	s_nop 0
	v_pk_add_f32 v[130:131], v[130:131], v[134:135] op_sel:[1,0] op_sel_hi:[0,1]
	v_mov_b32_e32 v133, v130
	v_pk_add_f32 v[136:137], v[132:133], v[138:139] neg_lo:[0,1] neg_hi:[0,1]
	v_mov_b32_e32 v129, v134
	v_sub_f32_e32 v131, v132, v136
	v_pk_add_f32 v[128:129], v[128:129], v[136:137] neg_lo:[0,1] neg_hi:[0,1]
	v_sub_f32_e32 v131, v138, v131
	v_add_f32_e32 v128, v128, v131
	v_add_f32_e32 v128, v128, v129
	v_add_f32_e32 v128, v130, v128
	v_cndmask_b32_e32 v128, v166, v128, vcc
	v_cmp_lt_f32_e64 vcc, |v153|, s29
	s_nop 1
	v_cndmask_b32_e32 v128, v128, v153, vcc
	v_sub_f32_e32 v130, v151, v128
	v_lshl_or_b32 v128, v152, 3, v158
	v_mul_hi_i32_i24_e32 v129, 0x8200, v128
	v_mul_i32_i24_e32 v128, 0x8200, v128
	v_ashrrev_i32_e32 v151, 31, v150
	v_lshl_add_u64 v[128:129], s[48:49], 0, v[128:129]
	v_lshl_add_u64 v[128:129], v[150:151], 2, v[128:129]
	global_store_dword v[128:129], v130, off
	s_branch .LBB0_70
